# speedup vs baseline: 1.0230x; 1.0026x over previous
; __device__ __forceinline__ float bf2f(u16 v) { return __uint_as_float(((uint32_t)v) << 16); }
; __device__ __forceinline__ void load_pair16(const u16* rowbase, const int fq, uint2& a, uint2& b) {
;   const uint4 v = *(const uint4*)(rowbase + (fq & 1) * 16 + (fq >> 1) * 8);
;   auto r0 = __builtin_amdgcn_permlane16_swap(v.x, v.z, false, false);
;   auto r1 = __builtin_amdgcn_permlane16_swap(v.y, v.w, false, false);
;   a = make_uint2(r0[0], r1[0]); b = make_uint2(r0[1], r1[1]);
; }
; template <bool MID>
; __device__ __forceinline__ void gemm_main8(const int tid, const u16* __restrict__ Ab, int lda, const u16* __restrict__ Bb, int ldb,
;                                            int nkt, char* shm, f32x4 (&acc)[8][4], const u16* __restrict__ midp = nullptr, int tmid = -1) {
;     ...
;     if (MID && t == tmid) {
;       unsigned voff = (unsigned)((wr * 128 + fr) * 1024 + wc * 64);
;       asm volatile("" : "+v"(voff));
; #pragma unroll
;       for (int m = 0; m < 8; ++m) {
; #pragma unroll
;         for (int np = 0; np < 2; ++np) {
;           uint2 rr[2];
;           load_pair16(midp + (voff + (unsigned)(m * 16 * 1024 + np * 32)), fq, rr[0], rr[1]);
; #pragma unroll
;           for (int q = 0; q < 2; ++q) {
;             const int n = np * 2 + q;
;             acc[m][n][0] *= bf2f((u16)(rr[q].x & 0xffffu)); acc[m][n][1] *= bf2f((u16)(rr[q].x >> 16));
;             acc[m][n][2] *= bf2f((u16)(rr[q].y & 0xffffu)); acc[m][n][3] *= bf2f((u16)(rr[q].y >> 16));
;           }
;         }
;         if (m & 1) __builtin_amdgcn_sched_barrier(0);
;       }
;     }
.LBB0_388:
	s_cmpk_lg_i32 s10, 0x400
	s_cbranch_scc1 .LBB0_387
	v_mov_b32_e32 v0, v159
	v_mov_b32_e32 v244, v159
	v_mov_b32_e32 v245, v1
	v_lshl_add_u64 v[244:245], v[244:245], 1, v[142:143]
	global_load_dwordx4 v[180:183], v[244:245], off
	v_add_u32_e32 v244, 0x20, v159
	v_mov_b32_e32 v245, v1
	v_lshl_add_u64 v[244:245], v[244:245], 1, v[142:143]
	global_load_dwordx4 v[184:187], v[244:245], off
	v_add_u32_e32 v244, 0x4000, v159
	v_mov_b32_e32 v245, v1
	v_lshl_add_u64 v[244:245], v[244:245], 1, v[142:143]
	global_load_dwordx4 v[188:191], v[244:245], off
	v_add_u32_e32 v244, 0x4020, v159
	v_mov_b32_e32 v245, v1
	v_lshl_add_u64 v[244:245], v[244:245], 1, v[142:143]
	global_load_dwordx4 v[192:195], v[244:245], off
	v_add_u32_e32 v244, 0x8000, v159
	v_mov_b32_e32 v245, v1
	v_lshl_add_u64 v[244:245], v[244:245], 1, v[142:143]
	global_load_dwordx4 v[196:199], v[244:245], off
	v_add_u32_e32 v244, 0x8020, v159
	v_mov_b32_e32 v245, v1
	v_lshl_add_u64 v[244:245], v[244:245], 1, v[142:143]
	global_load_dwordx4 v[200:203], v[244:245], off
	v_add_u32_e32 v244, 0xc000, v159
	v_mov_b32_e32 v245, v1
	v_lshl_add_u64 v[244:245], v[244:245], 1, v[142:143]
	global_load_dwordx4 v[204:207], v[244:245], off
	v_add_u32_e32 v244, 0xc020, v159
	v_mov_b32_e32 v245, v1
	v_lshl_add_u64 v[244:245], v[244:245], 1, v[142:143]
	global_load_dwordx4 v[208:211], v[244:245], off
	v_add_u32_e32 v244, 0x10000, v159
	v_mov_b32_e32 v245, v1
	v_lshl_add_u64 v[244:245], v[244:245], 1, v[142:143]
	global_load_dwordx4 v[212:215], v[244:245], off
	v_add_u32_e32 v244, 0x10020, v159
	v_mov_b32_e32 v245, v1
	v_lshl_add_u64 v[244:245], v[244:245], 1, v[142:143]
	global_load_dwordx4 v[216:219], v[244:245], off
	v_add_u32_e32 v244, 0x14000, v159
	v_mov_b32_e32 v245, v1
	v_lshl_add_u64 v[244:245], v[244:245], 1, v[142:143]
	global_load_dwordx4 v[220:223], v[244:245], off
	v_add_u32_e32 v244, 0x14020, v159
	v_mov_b32_e32 v245, v1
	v_lshl_add_u64 v[244:245], v[244:245], 1, v[142:143]
	global_load_dwordx4 v[224:227], v[244:245], off
	v_add_u32_e32 v244, 0x18000, v159
	v_mov_b32_e32 v245, v1
	v_lshl_add_u64 v[244:245], v[244:245], 1, v[142:143]
	global_load_dwordx4 v[228:231], v[244:245], off
	v_add_u32_e32 v244, 0x18020, v159
	v_mov_b32_e32 v245, v1
	v_lshl_add_u64 v[244:245], v[244:245], 1, v[142:143]
	global_load_dwordx4 v[232:235], v[244:245], off
	v_add_u32_e32 v244, 0x1c000, v159
	v_mov_b32_e32 v245, v1
	v_lshl_add_u64 v[244:245], v[244:245], 1, v[142:143]
	global_load_dwordx4 v[236:239], v[244:245], off
	v_add_u32_e32 v244, 0x1c020, v159
	v_mov_b32_e32 v245, v1
	v_lshl_add_u64 v[244:245], v[244:245], 1, v[142:143]
	global_load_dwordx4 v[240:243], v[244:245], off
	s_nop 0
	v_lshl_add_u64 v[2:3], v[0:1], 1, v[142:143]
	s_waitcnt vmcnt(15)
	v_mov_b32_e32 v136, v180
	v_mov_b32_e32 v137, v181
	v_mov_b32_e32 v138, v182
	v_mov_b32_e32 v139, v183
	s_nop 1
	v_permlane16_swap_b32_e32 v136, v138
	v_lshlrev_b32_e32 v2, 16, v136
	v_and_b32_e32 v3, 0xffff0000, v136
	v_permlane16_swap_b32_e32 v137, v139
	v_pk_mul_f32 v[128:129], v[128:129], v[2:3]
	v_lshlrev_b32_e32 v2, 16, v138
	v_and_b32_e32 v3, 0xffff0000, v138
	v_lshlrev_b32_e32 v136, 16, v137
	v_and_b32_e32 v137, 0xffff0000, v137
	v_pk_mul_f32 v[124:125], v[124:125], v[2:3]
	v_add_u32_e32 v2, 32, v0
	v_mov_b32_e32 v3, v1
	v_pk_mul_f32 v[130:131], v[130:131], v[136:137]
	v_lshlrev_b32_e32 v136, 16, v139
	v_and_b32_e32 v137, 0xffff0000, v139
	v_lshl_add_u64 v[2:3], v[2:3], 1, v[142:143]
	v_pk_mul_f32 v[126:127], v[126:127], v[136:137]
	s_waitcnt vmcnt(14)
	v_mov_b32_e32 v136, v184
	v_mov_b32_e32 v137, v185
	v_mov_b32_e32 v138, v186
	v_mov_b32_e32 v139, v187
	s_nop 1
	v_permlane16_swap_b32_e32 v136, v138
	v_lshlrev_b32_e32 v2, 16, v136
	v_and_b32_e32 v3, 0xffff0000, v136
	v_permlane16_swap_b32_e32 v137, v139
	v_pk_mul_f32 v[96:97], v[96:97], v[2:3]
	v_lshlrev_b32_e32 v2, 16, v138
	v_and_b32_e32 v3, 0xffff0000, v138
	v_lshlrev_b32_e32 v136, 16, v137
	v_and_b32_e32 v137, 0xffff0000, v137
	v_pk_mul_f32 v[92:93], v[92:93], v[2:3]
	v_add_u32_e32 v2, 0x4000, v0
	v_mov_b32_e32 v3, v1
	v_pk_mul_f32 v[98:99], v[98:99], v[136:137]
	v_lshlrev_b32_e32 v136, 16, v139
	v_and_b32_e32 v137, 0xffff0000, v139
	v_lshl_add_u64 v[2:3], v[2:3], 1, v[142:143]
	v_pk_mul_f32 v[94:95], v[94:95], v[136:137]
	s_waitcnt vmcnt(13)
	v_mov_b32_e32 v136, v188
	v_mov_b32_e32 v137, v189
	v_mov_b32_e32 v138, v190
	v_mov_b32_e32 v139, v191
	s_nop 1
	v_permlane16_swap_b32_e32 v136, v138
	v_lshlrev_b32_e32 v2, 16, v136
	v_and_b32_e32 v3, 0xffff0000, v136
	v_permlane16_swap_b32_e32 v137, v139
	v_pk_mul_f32 v[120:121], v[120:121], v[2:3]
	v_lshlrev_b32_e32 v2, 16, v138
	v_and_b32_e32 v3, 0xffff0000, v138
	v_lshlrev_b32_e32 v136, 16, v137
	v_and_b32_e32 v137, 0xffff0000, v137
	v_pk_mul_f32 v[116:117], v[116:117], v[2:3]
	v_add_u32_e32 v2, 0x4020, v0
	v_mov_b32_e32 v3, v1
	v_pk_mul_f32 v[122:123], v[122:123], v[136:137]
	v_lshlrev_b32_e32 v136, 16, v139
	v_and_b32_e32 v137, 0xffff0000, v139
	v_lshl_add_u64 v[2:3], v[2:3], 1, v[142:143]
	v_pk_mul_f32 v[118:119], v[118:119], v[136:137]
	s_waitcnt vmcnt(12)
	v_mov_b32_e32 v136, v192
	v_mov_b32_e32 v137, v193
	v_mov_b32_e32 v138, v194
	v_mov_b32_e32 v139, v195
	s_nop 1
	v_permlane16_swap_b32_e32 v136, v138
	v_permlane16_swap_b32_e32 v137, v139
	v_lshlrev_b32_e32 v2, 16, v136
	v_and_b32_e32 v3, 0xffff0000, v136
	v_lshlrev_b32_e32 v136, 16, v137
	v_and_b32_e32 v137, 0xffff0000, v137
	v_pk_mul_f32 v[90:91], v[90:91], v[136:137]
	v_pk_mul_f32 v[88:89], v[88:89], v[2:3]
	v_lshlrev_b32_e32 v2, 16, v138
	v_and_b32_e32 v3, 0xffff0000, v138
	v_lshlrev_b32_e32 v136, 16, v139
	v_and_b32_e32 v137, 0xffff0000, v139
	v_pk_mul_f32 v[86:87], v[86:87], v[136:137]
	v_pk_mul_f32 v[84:85], v[84:85], v[2:3]
	v_add_u32_e32 v2, 0x8000, v0
	v_mov_b32_e32 v3, v1
	v_lshl_add_u64 v[2:3], v[2:3], 1, v[142:143]
	s_waitcnt vmcnt(11)
; __device__ __forceinline__ float bf2f(u16 v) { return __uint_as_float(((uint32_t)v) << 16); }
; __device__ __forceinline__ void load_pair16(const u16* rowbase, const int fq, uint2& a, uint2& b) {
;   const uint4 v = *(const uint4*)(rowbase + (fq & 1) * 16 + (fq >> 1) * 8);
;   auto r0 = __builtin_amdgcn_permlane16_swap(v.x, v.z, false, false);
;   auto r1 = __builtin_amdgcn_permlane16_swap(v.y, v.w, false, false);
;   a = make_uint2(r0[0], r1[0]); b = make_uint2(r0[1], r1[1]);
; }
; template <bool MID>
; __device__ __forceinline__ void gemm_main8(const int tid, const u16* __restrict__ Ab, int lda, const u16* __restrict__ Bb, int ldb,
;                                            int nkt, char* shm, f32x4 (&acc)[8][4], const u16* __restrict__ midp = nullptr, int tmid = -1) {
;     ...
;       for (int m = 0; m < 8; ++m) {
; #pragma unroll
;         for (int np = 0; np < 2; ++np) {
;           uint2 rr[2];
;           load_pair16(midp + (voff + (unsigned)(m * 16 * 1024 + np * 32)), fq, rr[0], rr[1]);
; #pragma unroll
;           for (int q = 0; q < 2; ++q) {
;             const int n = np * 2 + q;
;             acc[m][n][0] *= bf2f((u16)(rr[q].x & 0xffffu)); acc[m][n][1] *= bf2f((u16)(rr[q].x >> 16));
;             acc[m][n][2] *= bf2f((u16)(rr[q].y & 0xffffu)); acc[m][n][3] *= bf2f((u16)(rr[q].y >> 16));
;           }
;         }
;         if (m & 1) __builtin_amdgcn_sched_barrier(0);
	v_mov_b32_e32 v136, v196
	v_mov_b32_e32 v137, v197
	v_mov_b32_e32 v138, v198
	v_mov_b32_e32 v139, v199
	s_nop 1
	v_permlane16_swap_b32_e32 v136, v138
	v_lshlrev_b32_e32 v2, 16, v136
	v_and_b32_e32 v3, 0xffff0000, v136
	v_permlane16_swap_b32_e32 v137, v139
	v_pk_mul_f32 v[112:113], v[112:113], v[2:3]
	v_lshlrev_b32_e32 v2, 16, v138
	v_and_b32_e32 v3, 0xffff0000, v138
	v_lshlrev_b32_e32 v136, 16, v137
	v_and_b32_e32 v137, 0xffff0000, v137
	v_pk_mul_f32 v[108:109], v[108:109], v[2:3]
	v_add_u32_e32 v2, 0x8020, v0
	v_mov_b32_e32 v3, v1
	v_pk_mul_f32 v[114:115], v[114:115], v[136:137]
	v_lshlrev_b32_e32 v136, 16, v139
	v_and_b32_e32 v137, 0xffff0000, v139
	v_lshl_add_u64 v[2:3], v[2:3], 1, v[142:143]
	v_pk_mul_f32 v[110:111], v[110:111], v[136:137]
	s_waitcnt vmcnt(10)
	v_mov_b32_e32 v136, v200
	v_mov_b32_e32 v137, v201
	v_mov_b32_e32 v138, v202
	v_mov_b32_e32 v139, v203
	s_nop 1
	v_permlane16_swap_b32_e32 v136, v138
	v_lshlrev_b32_e32 v2, 16, v136
	v_and_b32_e32 v3, 0xffff0000, v136
	v_permlane16_swap_b32_e32 v137, v139
	v_pk_mul_f32 v[80:81], v[80:81], v[2:3]
	v_lshlrev_b32_e32 v2, 16, v138
	v_and_b32_e32 v3, 0xffff0000, v138
	v_lshlrev_b32_e32 v136, 16, v137
	v_and_b32_e32 v137, 0xffff0000, v137
	v_pk_mul_f32 v[76:77], v[76:77], v[2:3]
	v_add_u32_e32 v2, 0xc000, v0
	v_mov_b32_e32 v3, v1
	v_pk_mul_f32 v[82:83], v[82:83], v[136:137]
	v_lshlrev_b32_e32 v136, 16, v139
	v_and_b32_e32 v137, 0xffff0000, v139
	v_lshl_add_u64 v[2:3], v[2:3], 1, v[142:143]
	v_pk_mul_f32 v[78:79], v[78:79], v[136:137]
	s_waitcnt vmcnt(9)
	v_mov_b32_e32 v136, v204
	v_mov_b32_e32 v137, v205
	v_mov_b32_e32 v138, v206
	v_mov_b32_e32 v139, v207
	s_nop 1
	v_permlane16_swap_b32_e32 v136, v138
	v_lshlrev_b32_e32 v2, 16, v136
	v_and_b32_e32 v3, 0xffff0000, v136
	v_permlane16_swap_b32_e32 v137, v139
	v_pk_mul_f32 v[104:105], v[104:105], v[2:3]
	v_lshlrev_b32_e32 v2, 16, v138
	v_and_b32_e32 v3, 0xffff0000, v138
	v_lshlrev_b32_e32 v136, 16, v137
	v_and_b32_e32 v137, 0xffff0000, v137
	v_pk_mul_f32 v[100:101], v[100:101], v[2:3]
	v_add_u32_e32 v2, 0xc020, v0
	v_mov_b32_e32 v3, v1
	v_pk_mul_f32 v[106:107], v[106:107], v[136:137]
	v_lshlrev_b32_e32 v136, 16, v139
	v_and_b32_e32 v137, 0xffff0000, v139
	v_lshl_add_u64 v[2:3], v[2:3], 1, v[142:143]
	v_pk_mul_f32 v[102:103], v[102:103], v[136:137]
	s_waitcnt vmcnt(8)
	v_mov_b32_e32 v136, v208
	v_mov_b32_e32 v137, v209
	v_mov_b32_e32 v138, v210
	v_mov_b32_e32 v139, v211
	s_nop 1
	v_permlane16_swap_b32_e32 v136, v138
	v_permlane16_swap_b32_e32 v137, v139
	v_lshlrev_b32_e32 v2, 16, v136
	v_and_b32_e32 v3, 0xffff0000, v136
	v_lshlrev_b32_e32 v136, 16, v137
	v_and_b32_e32 v137, 0xffff0000, v137
	v_pk_mul_f32 v[74:75], v[74:75], v[136:137]
	v_pk_mul_f32 v[72:73], v[72:73], v[2:3]
	v_lshlrev_b32_e32 v2, 16, v138
	v_and_b32_e32 v3, 0xffff0000, v138
	v_lshlrev_b32_e32 v136, 16, v139
	v_and_b32_e32 v137, 0xffff0000, v139
	v_pk_mul_f32 v[70:71], v[70:71], v[136:137]
	v_pk_mul_f32 v[68:69], v[68:69], v[2:3]
	v_add_u32_e32 v2, 0x10000, v0
	v_mov_b32_e32 v3, v1
	v_lshl_add_u64 v[2:3], v[2:3], 1, v[142:143]
	s_waitcnt vmcnt(7)
	v_mov_b32_e32 v136, v212
	v_mov_b32_e32 v137, v213
	v_mov_b32_e32 v138, v214
	v_mov_b32_e32 v139, v215
	s_nop 1
	v_permlane16_swap_b32_e32 v136, v138
	v_lshlrev_b32_e32 v2, 16, v136
	v_and_b32_e32 v3, 0xffff0000, v136
	v_permlane16_swap_b32_e32 v137, v139
	v_pk_mul_f32 v[64:65], v[64:65], v[2:3]
	v_lshlrev_b32_e32 v2, 16, v138
	v_and_b32_e32 v3, 0xffff0000, v138
	v_lshlrev_b32_e32 v136, 16, v137
	v_and_b32_e32 v137, 0xffff0000, v137
	v_pk_mul_f32 v[60:61], v[60:61], v[2:3]
	v_add_u32_e32 v2, 0x10020, v0
	v_mov_b32_e32 v3, v1
	v_pk_mul_f32 v[66:67], v[66:67], v[136:137]
	v_lshlrev_b32_e32 v136, 16, v139
	v_and_b32_e32 v137, 0xffff0000, v139
	v_lshl_add_u64 v[2:3], v[2:3], 1, v[142:143]
	v_pk_mul_f32 v[62:63], v[62:63], v[136:137]
	s_waitcnt vmcnt(6)
	v_mov_b32_e32 v136, v216
	v_mov_b32_e32 v137, v217
	v_mov_b32_e32 v138, v218
	v_mov_b32_e32 v139, v219
	s_nop 1
	v_permlane16_swap_b32_e32 v136, v138
	v_lshlrev_b32_e32 v2, 16, v136
	v_and_b32_e32 v3, 0xffff0000, v136
	v_permlane16_swap_b32_e32 v137, v139
	v_pk_mul_f32 v[40:41], v[40:41], v[2:3]
	v_lshlrev_b32_e32 v2, 16, v138
	v_and_b32_e32 v3, 0xffff0000, v138
	v_lshlrev_b32_e32 v136, 16, v137
	v_and_b32_e32 v137, 0xffff0000, v137
	v_pk_mul_f32 v[36:37], v[36:37], v[2:3]
	v_add_u32_e32 v2, 0x14000, v0
	v_mov_b32_e32 v3, v1
	v_pk_mul_f32 v[42:43], v[42:43], v[136:137]
	v_lshlrev_b32_e32 v136, 16, v139
	v_and_b32_e32 v137, 0xffff0000, v139
	v_lshl_add_u64 v[2:3], v[2:3], 1, v[142:143]
	v_pk_mul_f32 v[38:39], v[38:39], v[136:137]
	s_waitcnt vmcnt(5)
; __device__ __forceinline__ float bf2f(u16 v) { return __uint_as_float(((uint32_t)v) << 16); }
; __device__ __forceinline__ void load_pair16(const u16* rowbase, const int fq, uint2& a, uint2& b) {
;   const uint4 v = *(const uint4*)(rowbase + (fq & 1) * 16 + (fq >> 1) * 8);
;   auto r0 = __builtin_amdgcn_permlane16_swap(v.x, v.z, false, false);
;   auto r1 = __builtin_amdgcn_permlane16_swap(v.y, v.w, false, false);
;   a = make_uint2(r0[0], r1[0]); b = make_uint2(r0[1], r1[1]);
; }
; template <bool MID>
; __device__ __forceinline__ void gemm_main8(const int tid, const u16* __restrict__ Ab, int lda, const u16* __restrict__ Bb, int ldb,
;                                            int nkt, char* shm, f32x4 (&acc)[8][4], const u16* __restrict__ midp = nullptr, int tmid = -1) {
;     ...
;       for (int m = 0; m < 8; ++m) {
; #pragma unroll
;         for (int np = 0; np < 2; ++np) {
;           uint2 rr[2];
;           load_pair16(midp + (voff + (unsigned)(m * 16 * 1024 + np * 32)), fq, rr[0], rr[1]);
; #pragma unroll
;           for (int q = 0; q < 2; ++q) {
;             const int n = np * 2 + q;
;             acc[m][n][0] *= bf2f((u16)(rr[q].x & 0xffffu)); acc[m][n][1] *= bf2f((u16)(rr[q].x >> 16));
;             acc[m][n][2] *= bf2f((u16)(rr[q].y & 0xffffu)); acc[m][n][3] *= bf2f((u16)(rr[q].y >> 16));
;           }
;         }
;         if (m & 1) __builtin_amdgcn_sched_barrier(0);
	v_mov_b32_e32 v136, v220
	v_mov_b32_e32 v137, v221
	v_mov_b32_e32 v138, v222
	v_mov_b32_e32 v139, v223
	s_nop 1
	v_permlane16_swap_b32_e32 v136, v138
	v_lshlrev_b32_e32 v2, 16, v136
	v_and_b32_e32 v3, 0xffff0000, v136
	v_permlane16_swap_b32_e32 v137, v139
	v_pk_mul_f32 v[56:57], v[56:57], v[2:3]
	v_lshlrev_b32_e32 v2, 16, v138
	v_and_b32_e32 v3, 0xffff0000, v138
	v_lshlrev_b32_e32 v136, 16, v137
	v_and_b32_e32 v137, 0xffff0000, v137
	v_pk_mul_f32 v[52:53], v[52:53], v[2:3]
	v_add_u32_e32 v2, 0x14020, v0
	v_mov_b32_e32 v3, v1
	v_pk_mul_f32 v[58:59], v[58:59], v[136:137]
	v_lshlrev_b32_e32 v136, 16, v139
	v_and_b32_e32 v137, 0xffff0000, v139
	v_lshl_add_u64 v[2:3], v[2:3], 1, v[142:143]
	v_pk_mul_f32 v[54:55], v[54:55], v[136:137]
	s_waitcnt vmcnt(4)
	v_mov_b32_e32 v136, v224
	v_mov_b32_e32 v137, v225
	v_mov_b32_e32 v138, v226
	v_mov_b32_e32 v139, v227
	s_nop 1
	v_permlane16_swap_b32_e32 v136, v138
	v_permlane16_swap_b32_e32 v137, v139
	v_lshlrev_b32_e32 v2, 16, v136
	v_and_b32_e32 v3, 0xffff0000, v136
	v_lshlrev_b32_e32 v136, 16, v137
	v_and_b32_e32 v137, 0xffff0000, v137
	v_pk_mul_f32 v[26:27], v[26:27], v[136:137]
	v_pk_mul_f32 v[24:25], v[24:25], v[2:3]
	v_lshlrev_b32_e32 v2, 16, v138
	v_and_b32_e32 v3, 0xffff0000, v138
	v_lshlrev_b32_e32 v136, 16, v139
	v_and_b32_e32 v137, 0xffff0000, v139
	v_pk_mul_f32 v[22:23], v[22:23], v[136:137]
	v_pk_mul_f32 v[20:21], v[20:21], v[2:3]
	v_add_u32_e32 v2, 0x18000, v0
	v_mov_b32_e32 v3, v1
	v_lshl_add_u64 v[2:3], v[2:3], 1, v[142:143]
	s_waitcnt vmcnt(3)
	v_mov_b32_e32 v136, v228
	v_mov_b32_e32 v137, v229
	v_mov_b32_e32 v138, v230
	v_mov_b32_e32 v139, v231
	s_nop 1
	v_permlane16_swap_b32_e32 v136, v138
	v_lshlrev_b32_e32 v2, 16, v136
	v_and_b32_e32 v3, 0xffff0000, v136
	v_permlane16_swap_b32_e32 v137, v139
	v_pk_mul_f32 v[48:49], v[48:49], v[2:3]
	v_lshlrev_b32_e32 v2, 16, v138
	v_and_b32_e32 v3, 0xffff0000, v138
	v_lshlrev_b32_e32 v136, 16, v137
	v_and_b32_e32 v137, 0xffff0000, v137
	v_pk_mul_f32 v[44:45], v[44:45], v[2:3]
	v_add_u32_e32 v2, 0x18020, v0
	v_mov_b32_e32 v3, v1
	v_pk_mul_f32 v[50:51], v[50:51], v[136:137]
	v_lshlrev_b32_e32 v136, 16, v139
	v_and_b32_e32 v137, 0xffff0000, v139
	v_lshl_add_u64 v[2:3], v[2:3], 1, v[142:143]
	v_pk_mul_f32 v[46:47], v[46:47], v[136:137]
	s_waitcnt vmcnt(2)
	v_mov_b32_e32 v136, v232
	v_mov_b32_e32 v137, v233
	v_mov_b32_e32 v138, v234
	v_mov_b32_e32 v139, v235
	s_nop 1
	v_permlane16_swap_b32_e32 v136, v138
	v_lshlrev_b32_e32 v2, 16, v136
	v_and_b32_e32 v3, 0xffff0000, v136
	v_permlane16_swap_b32_e32 v137, v139
	v_pk_mul_f32 v[16:17], v[16:17], v[2:3]
	v_lshlrev_b32_e32 v2, 16, v138
	v_and_b32_e32 v3, 0xffff0000, v138
	v_lshlrev_b32_e32 v136, 16, v137
	v_and_b32_e32 v137, 0xffff0000, v137
	v_pk_mul_f32 v[12:13], v[12:13], v[2:3]
	v_add_u32_e32 v2, 0x1c000, v0
	v_mov_b32_e32 v3, v1
	v_pk_mul_f32 v[18:19], v[18:19], v[136:137]
	v_lshlrev_b32_e32 v136, 16, v139
	v_and_b32_e32 v137, 0xffff0000, v139
	v_lshl_add_u64 v[2:3], v[2:3], 1, v[142:143]
	v_pk_mul_f32 v[14:15], v[14:15], v[136:137]
	v_add_u32_e32 v0, 0x1c020, v0
	s_waitcnt vmcnt(1)
	v_mov_b32_e32 v136, v236
	v_mov_b32_e32 v137, v237
	v_mov_b32_e32 v138, v238
	v_mov_b32_e32 v139, v239
	s_nop 1
	v_permlane16_swap_b32_e32 v136, v138
	v_permlane16_swap_b32_e32 v137, v139
	v_lshlrev_b32_e32 v2, 16, v136
	v_and_b32_e32 v3, 0xffff0000, v136
	v_lshlrev_b32_e32 v136, 16, v137
	v_and_b32_e32 v137, 0xffff0000, v137
	v_pk_mul_f32 v[32:33], v[32:33], v[2:3]
	v_lshlrev_b32_e32 v2, 16, v138
	v_and_b32_e32 v3, 0xffff0000, v138
	v_pk_mul_f32 v[34:35], v[34:35], v[136:137]
	v_lshlrev_b32_e32 v136, 16, v139
	v_and_b32_e32 v137, 0xffff0000, v139
	v_pk_mul_f32 v[28:29], v[28:29], v[2:3]
	v_lshl_add_u64 v[2:3], v[0:1], 1, v[142:143]
	v_pk_mul_f32 v[30:31], v[30:31], v[136:137]
	s_waitcnt vmcnt(0)
	v_mov_b32_e32 v136, v240
	v_mov_b32_e32 v137, v241
	v_mov_b32_e32 v138, v242
	v_mov_b32_e32 v139, v243
	s_nop 1
	v_mov_b32_e32 v0, v138
	v_mov_b32_e32 v138, v139
	s_nop 0
	v_permlane16_swap_b32_e32 v136, v0
	v_permlane16_swap_b32_e32 v137, v138
	v_lshlrev_b32_e32 v2, 16, v136
	v_and_b32_e32 v3, 0xffff0000, v136
	v_lshlrev_b32_e32 v136, 16, v137
	v_and_b32_e32 v137, 0xffff0000, v137
	v_pk_mul_f32 v[10:11], v[10:11], v[136:137]
	v_pk_mul_f32 v[8:9], v[8:9], v[2:3]
	v_lshlrev_b32_e32 v2, 16, v0
	v_and_b32_e32 v3, 0xffff0000, v0
	v_lshlrev_b32_e32 v136, 16, v138
	v_and_b32_e32 v137, 0xffff0000, v138
	v_pk_mul_f32 v[6:7], v[6:7], v[136:137]
	v_pk_mul_f32 v[4:5], v[4:5], v[2:3]
	s_branch .LBB0_387
